# static s_setprio 1 for waves 4-7 during both attention phases (breaks MFMA/VALU lockstep)
# speedup vs baseline: 1.0023x; 1.0023x over previous
.LBB0_359:
	s_setprio 0
	s_cmp_gt_i32 s21, 4
	s_cselect_b64 s[4:5], -1, 0
	s_and_b64 s[6:7], s[8:9], s[4:5]
	s_andn2_b64 vcc, exec, s[6:7]
	s_cbranch_vccnz .LBB0_427
	s_cmp_eq_u32 s22, 0
	s_cbranch_scc1 .LBB0_372
	v_lshrrev_b32_e32 v2, 20, v0
	v_lshrrev_b32_e32 v3, 10, v0
	v_or_b32_e32 v2, v3, v2
	s_movk_i32 s3, 0x3ff
	v_and_or_b32 v2, v2, s3, v1
	v_cmp_eq_u32_e32 vcc, 0, v2
	s_barrier
	s_and_saveexec_b64 s[6:7], vcc
	s_cbranch_execz .LBB0_371
	buffer_wbl2 sc1
	s_waitcnt vmcnt(0)
	s_load_dwordx2 s[8:9], s[40:41], 0x58
	v_mov_b32_e32 v4, 0
	s_mov_b64 s[10:11], exec
	v_mbcnt_lo_u32_b32 v3, s10, 0
	v_mbcnt_hi_u32_b32 v3, s11, v3
	s_waitcnt lgkmcnt(0)
	global_load_dword v2, v4, s[8:9] offset:40
	v_cmp_eq_u32_e32 vcc, 0, v3
	s_and_saveexec_b64 s[12:13], vcc
	s_cbranch_execz .LBB0_364
	s_bcnt1_i32_b64 s3, s[10:11]
	v_mov_b32_e32 v5, s3
	global_atomic_add v5, v4, v5, s[8:9] offset:32 sc0

.LBB0_426:
.LBB0_427:
	v_readfirstlane_b32 s98, v1
	s_nop 3
	s_lshr_b32 s98, s98, 8
	s_cmp_eq_u32 s98, 0
	s_cbranch_scc1 .Lprio_done_4
	s_setprio 1

.LBB0_1525:
	s_setprio 0
	s_cmp_gt_i32 s21, 12
	s_cselect_b64 s[4:5], -1, 0
	s_and_b64 s[6:7], s[8:9], s[4:5]
	s_andn2_b64 vcc, exec, s[6:7]
	s_cbranch_vccnz .LBB0_1593
	s_cmp_eq_u32 s22, 0
	s_cbranch_scc1 .LBB0_1538
	v_lshrrev_b32_e32 v2, 20, v0
	s_waitcnt lgkmcnt(0)
	v_lshrrev_b32_e32 v3, 10, v0
	v_or_b32_e32 v2, v3, v2
	s_movk_i32 s3, 0x3ff
	v_and_or_b32 v2, v2, s3, v1
	v_cmp_eq_u32_e32 vcc, 0, v2
	s_barrier
	s_and_saveexec_b64 s[6:7], vcc
	s_cbranch_execz .LBB0_1537
	buffer_wbl2 sc1
	s_waitcnt vmcnt(0)
	s_load_dwordx2 s[8:9], s[40:41], 0x58
	v_mov_b32_e32 v4, 0
	s_mov_b64 s[10:11], exec
	v_mbcnt_lo_u32_b32 v3, s10, 0
	v_mbcnt_hi_u32_b32 v3, s11, v3
	s_waitcnt lgkmcnt(0)
	global_load_dword v2, v4, s[8:9] offset:40
	v_cmp_eq_u32_e32 vcc, 0, v3
	s_and_saveexec_b64 s[12:13], vcc
	s_cbranch_execz .LBB0_1530
	s_bcnt1_i32_b64 s3, s[10:11]
	v_mov_b32_e32 v5, s3
	global_atomic_add v5, v4, v5, s[8:9] offset:32 sc0

.LBB0_1593:
	v_readfirstlane_b32 s98, v1
	s_nop 3
	s_lshr_b32 s98, s98, 8
	s_cmp_eq_u32 s98, 0
	s_cbranch_scc1 .Lprio_done_12
	s_setprio 1

	.amdhsa_kernel _Z8yoco_fwd4Args
		.amdhsa_group_segment_fixed_size 0
		.amdhsa_private_segment_fixed_size 0
		.amdhsa_kernarg_size 448
		.amdhsa_user_sgpr_count 2
		.amdhsa_user_sgpr_dispatch_ptr 0
		.amdhsa_user_sgpr_queue_ptr 0
		.amdhsa_user_sgpr_kernarg_segment_ptr 1
		.amdhsa_user_sgpr_dispatch_id 0
		.amdhsa_user_sgpr_kernarg_preload_length 0
		.amdhsa_user_sgpr_kernarg_preload_offset 0
		.amdhsa_user_sgpr_private_segment_size 0
		.amdhsa_uses_dynamic_stack 0
		.amdhsa_enable_private_segment 0
		.amdhsa_system_sgpr_workgroup_id_x 1
		.amdhsa_system_sgpr_workgroup_id_y 0
		.amdhsa_system_sgpr_workgroup_id_z 0
		.amdhsa_system_sgpr_workgroup_info 0
		.amdhsa_system_vgpr_workitem_id 2
		.amdhsa_next_free_vgpr 256
		.amdhsa_next_free_sgpr 99
		.amdhsa_accum_offset 256
		.amdhsa_reserve_vcc 1
		.amdhsa_float_round_mode_32 0
		.amdhsa_float_round_mode_16_64 0
		.amdhsa_float_denorm_mode_32 3
		.amdhsa_float_denorm_mode_16_64 3
		.amdhsa_dx10_clamp 1
		.amdhsa_ieee_mode 1
		.amdhsa_fp16_overflow 0
		.amdhsa_tg_split 0
		.amdhsa_exception_fp_ieee_invalid_op 0
		.amdhsa_exception_fp_denorm_src 0
		.amdhsa_exception_fp_ieee_div_zero 0
		.amdhsa_exception_fp_ieee_overflow 0
		.amdhsa_exception_fp_ieee_underflow 0
		.amdhsa_exception_fp_ieee_inexact 0
		.amdhsa_exception_int_div_zero 0
	.end_amdhsa_kernel

amdhsa.kernels:
  - .agpr_count:     0
    .args:
      - .offset:         0
        .size:           192
        .value_kind:     by_value
      - .offset:         192
        .size:           4
        .value_kind:     hidden_block_count_x
      - .offset:         196
        .size:           4
        .value_kind:     hidden_block_count_y
      - .offset:         200
        .size:           4
        .value_kind:     hidden_block_count_z
      - .offset:         204
        .size:           2
        .value_kind:     hidden_group_size_x
      - .offset:         206
        .size:           2
        .value_kind:     hidden_group_size_y
      - .offset:         208
        .size:           2
        .value_kind:     hidden_group_size_z
      - .offset:         210
        .size:           2
        .value_kind:     hidden_remainder_x
      - .offset:         212
        .size:           2
        .value_kind:     hidden_remainder_y
      - .offset:         214
        .size:           2
        .value_kind:     hidden_remainder_z
      - .offset:         232
        .size:           8
        .value_kind:     hidden_global_offset_x
      - .offset:         240
        .size:           8
        .value_kind:     hidden_global_offset_y
      - .offset:         248
        .size:           8
        .value_kind:     hidden_global_offset_z
      - .offset:         256
        .size:           2
        .value_kind:     hidden_grid_dims
      - .offset:         280
        .size:           8
        .value_kind:     hidden_multigrid_sync_arg
      - .offset:         312
        .size:           4
        .value_kind:     hidden_dynamic_lds_size
    .group_segment_fixed_size: 0
    .kernarg_segment_align: 8
    .kernarg_segment_size: 448
    .language:       OpenCL C
    .language_version:
      - 2
      - 0
    .max_flat_workgroup_size: 512
    .name:           _Z8yoco_fwd4Args
    .private_segment_fixed_size: 0
    .sgpr_count:     105
    .sgpr_spill_count: 0
    .symbol:         _Z8yoco_fwd4Args.kd
    .uniform_work_group_size: 1
    .uses_dynamic_stack: false
    .vgpr_count:     256
    .vgpr_spill_count: 0
    .wavefront_size: 64
